# G2 and G3 epilogues regenerated as load pipelines (8-deep / 4-deep) into dead fragment regs; plus cg-sync replacement, GEMV rings, G6 pipeline
# speedup vs baseline: 1.0221x; 1.0006x over previous
; DI size_t pidx(size_t row, int col) { return (size_t)(col >> 8) * ((size_t)TH * 256) + row * 256 + (size_t)(col & 255); }
; DI float lo_f(unsigned u) { return __uint_as_float(u << 16); }
; DI float hi_f(unsigned u) { return __uint_as_float(u & 0xffff0000u); }
; DI unsigned pk2(float lo, float hi) { return pg8::cvt_pk_bf16(lo, hi); }
;     DI void operator()(const f32x4 (&acc)[2][2][4][2], const Unit& u, int wr, int wc, int fr, int fq) const {
;         const int row0 = u.pm * 256 + wr * 64 + fr, col0 = u.pn * 256 + wc * 32 + 8 * fq;
; #pragma unroll
;         for (int ai = 0; ai < 2; ++ai)
; #pragma unroll
;             for (int m = 0; m < 4; ++m) { const size_t r = (size_t)(row0 + ai * 128 + m * 16);
; #pragma unroll
;                 for (int bj = 0; bj < 2; ++bj) { const int c = col0 + bj * 128; const v4u g = *(const v4u*)(P + pidx(r, 7680 + c));
;                     const f32x4 v0 = acc[ai][bj][m][0], v1 = acc[ai][bj][m][1];
;                     v4u w; w.x = pk2(v0[0] * lo_f(g.x), v0[1] * hi_f(g.x)); w.y = pk2(v0[2] * lo_f(g.y), v0[3] * hi_f(g.y)); w.z = pk2(v1[0] * lo_f(g.z), v1[1] * hi_f(g.z)); w.w = pk2(v1[2] * lo_f(g.w), v1[3] * hi_f(g.w));
;                     *(v4u*)(Y + r * 1024 + c) = w; } }
.LBB0_562:
	s_lshl_b32 s2, s30, 8
	v_or_b32_e32 v154, s2, v138
	s_addk_i32 s2, 0x1e00
	s_ashr_i32 s2, s2, 8
	s_ashr_i32 s3, s2, 31
	v_lshl_add_u32 v146, s31, 8, v139
	s_lshl_b64 s[2:3], s[2:3], 24
	v_ashrrev_i32_e32 v147, 31, v146
	s_add_u32 s2, s86, s2
	v_lshlrev_b64 v[150:151], 9, v[146:147]
	s_addc_u32 s3, s87, s3
	v_lshl_add_u64 v[158:159], s[2:3], 0, v[150:151]
	v_lshlrev_b32_e32 v0, 1, v138
	v_lshl_add_u64 v[150:151], v[158:159], 0, v[0:1]
	s_andn2_b64 vcc, exec, s[4:5]
	v_lshlrev_b64 v[232:233], 11, v[146:147]
	v_ashrrev_i32_e32 v155, 31, v154
	v_lshl_add_u64 v[232:233], s[88:89], 0, v[232:233]
	v_lshlrev_b64 v[234:235], 1, v[154:155]
	v_lshl_add_u64 v[232:233], v[232:233], 0, v[234:235]
	global_load_dwordx4 v[200:203], v[150:151], off
	s_mov_b64 s[98:99], 0x100
	v_lshl_add_u64 v[234:235], v[150:151], 0, s[98:99]
	global_load_dwordx4 v[204:207], v[234:235], off
	s_mov_b64 s[98:99], 0x2000
	v_lshl_add_u64 v[234:235], v[150:151], 0, s[98:99]
	global_load_dwordx4 v[208:211], v[234:235], off
	s_mov_b64 s[98:99], 0x2100
	v_lshl_add_u64 v[234:235], v[150:151], 0, s[98:99]
	global_load_dwordx4 v[212:215], v[234:235], off
	s_mov_b64 s[98:99], 0x4000
	v_lshl_add_u64 v[234:235], v[150:151], 0, s[98:99]
	global_load_dwordx4 v[216:219], v[234:235], off
	s_mov_b64 s[98:99], 0x4100
	v_lshl_add_u64 v[234:235], v[150:151], 0, s[98:99]
	global_load_dwordx4 v[220:223], v[234:235], off
	s_mov_b64 s[98:99], 0x6000
	v_lshl_add_u64 v[234:235], v[150:151], 0, s[98:99]
	global_load_dwordx4 v[224:227], v[234:235], off
	s_mov_b64 s[98:99], 0x6100
	v_lshl_add_u64 v[234:235], v[150:151], 0, s[98:99]
	global_load_dwordx4 v[228:231], v[234:235], off
	s_waitcnt vmcnt(7)
	v_lshlrev_b32_e32 v238, 16, v200
	v_and_b32_e32 v239, 0xffff0000, v200
	v_mul_f32_e32 v126, v126, v238
	v_mul_f32_e32 v127, v127, v239
	v_cvt_pk_bf16_f32 v244, v126, v127
	v_lshlrev_b32_e32 v238, 16, v201
	v_and_b32_e32 v239, 0xffff0000, v201
	v_mul_f32_e32 v128, v128, v238
	v_mul_f32_e32 v129, v129, v239
	v_cvt_pk_bf16_f32 v245, v128, v129
	v_lshlrev_b32_e32 v238, 16, v202
	v_and_b32_e32 v239, 0xffff0000, v202
	v_mul_f32_e32 v122, v122, v238
	v_mul_f32_e32 v123, v123, v239
	v_cvt_pk_bf16_f32 v246, v122, v123
	v_lshlrev_b32_e32 v238, 16, v203
	v_and_b32_e32 v239, 0xffff0000, v203
	v_mul_f32_e32 v124, v124, v238
	v_mul_f32_e32 v125, v125, v239
	v_cvt_pk_bf16_f32 v247, v124, v125
	global_store_dwordx4 v[232:233], v[244:247], off
	s_mov_b64 s[98:99], 0x10000
	v_lshl_add_u64 v[234:235], v[150:151], 0, s[98:99]
	global_load_dwordx4 v[200:203], v[234:235], off
	s_waitcnt vmcnt(8)
	v_lshlrev_b32_e32 v238, 16, v204
	v_and_b32_e32 v239, 0xffff0000, v204
	v_mul_f32_e32 v118, v118, v238
	v_mul_f32_e32 v119, v119, v239
	v_cvt_pk_bf16_f32 v244, v118, v119
	v_lshlrev_b32_e32 v238, 16, v205
	v_and_b32_e32 v239, 0xffff0000, v205
	v_mul_f32_e32 v120, v120, v238
	v_mul_f32_e32 v121, v121, v239
	v_cvt_pk_bf16_f32 v245, v120, v121
	v_lshlrev_b32_e32 v238, 16, v206
	v_and_b32_e32 v239, 0xffff0000, v206
	v_mul_f32_e32 v114, v114, v238
	v_mul_f32_e32 v115, v115, v239
	v_cvt_pk_bf16_f32 v246, v114, v115
	v_lshlrev_b32_e32 v238, 16, v207
	v_and_b32_e32 v239, 0xffff0000, v207
	v_mul_f32_e32 v116, v116, v238
	v_mul_f32_e32 v117, v117, v239
	v_cvt_pk_bf16_f32 v247, v116, v117
	s_mov_b64 s[98:99], 0x100
	v_lshl_add_u64 v[236:237], v[232:233], 0, s[98:99]
	global_store_dwordx4 v[236:237], v[244:247], off
	s_mov_b64 s[98:99], 0x10100
	v_lshl_add_u64 v[234:235], v[150:151], 0, s[98:99]
	global_load_dwordx4 v[204:207], v[234:235], off
	s_waitcnt vmcnt(9)
	v_lshlrev_b32_e32 v238, 16, v208
	v_and_b32_e32 v239, 0xffff0000, v208
	v_mul_f32_e32 v110, v110, v238
	v_mul_f32_e32 v111, v111, v239
	v_cvt_pk_bf16_f32 v244, v110, v111
	v_lshlrev_b32_e32 v238, 16, v209
	v_and_b32_e32 v239, 0xffff0000, v209
	v_mul_f32_e32 v112, v112, v238
	v_mul_f32_e32 v113, v113, v239
	v_cvt_pk_bf16_f32 v245, v112, v113
	v_lshlrev_b32_e32 v238, 16, v210
	v_and_b32_e32 v239, 0xffff0000, v210
	v_mul_f32_e32 v106, v106, v238
	v_mul_f32_e32 v107, v107, v239
	v_cvt_pk_bf16_f32 v246, v106, v107
	v_lshlrev_b32_e32 v238, 16, v211
	v_and_b32_e32 v239, 0xffff0000, v211
	v_mul_f32_e32 v108, v108, v238
	v_mul_f32_e32 v109, v109, v239
	v_cvt_pk_bf16_f32 v247, v108, v109
	s_mov_b64 s[98:99], 0x8000
	v_lshl_add_u64 v[236:237], v[232:233], 0, s[98:99]
	global_store_dwordx4 v[236:237], v[244:247], off
	s_mov_b64 s[98:99], 0x12000
	v_lshl_add_u64 v[234:235], v[150:151], 0, s[98:99]
	global_load_dwordx4 v[208:211], v[234:235], off
	s_waitcnt vmcnt(10)
	v_lshlrev_b32_e32 v238, 16, v212
	v_and_b32_e32 v239, 0xffff0000, v212
	v_mul_f32_e32 v102, v102, v238
	v_mul_f32_e32 v103, v103, v239
	v_cvt_pk_bf16_f32 v244, v102, v103
	v_lshlrev_b32_e32 v238, 16, v213
	v_and_b32_e32 v239, 0xffff0000, v213
	v_mul_f32_e32 v104, v104, v238
	v_mul_f32_e32 v105, v105, v239
	v_cvt_pk_bf16_f32 v245, v104, v105
	v_lshlrev_b32_e32 v238, 16, v214
	v_and_b32_e32 v239, 0xffff0000, v214
	v_mul_f32_e32 v98, v98, v238
	v_mul_f32_e32 v99, v99, v239
	v_cvt_pk_bf16_f32 v246, v98, v99
	v_lshlrev_b32_e32 v238, 16, v215
	v_and_b32_e32 v239, 0xffff0000, v215
	v_mul_f32_e32 v100, v100, v238
	v_mul_f32_e32 v101, v101, v239
	v_cvt_pk_bf16_f32 v247, v100, v101
	s_mov_b64 s[98:99], 0x8100
	v_lshl_add_u64 v[236:237], v[232:233], 0, s[98:99]
	global_store_dwordx4 v[236:237], v[244:247], off
	s_mov_b64 s[98:99], 0x12100
	v_lshl_add_u64 v[234:235], v[150:151], 0, s[98:99]
	global_load_dwordx4 v[212:215], v[234:235], off
	s_waitcnt vmcnt(11)
; DI size_t pidx(size_t row, int col) { return (size_t)(col >> 8) * ((size_t)TH * 256) + row * 256 + (size_t)(col & 255); }
; DI float lo_f(unsigned u) { return __uint_as_float(u << 16); }
; DI float hi_f(unsigned u) { return __uint_as_float(u & 0xffff0000u); }
; DI unsigned pk2(float lo, float hi) { return pg8::cvt_pk_bf16(lo, hi); }
;     DI void operator()(const f32x4 (&acc)[2][2][4][2], const Unit& u, int wr, int wc, int fr, int fq) const {
;     ...
;         for (int ai = 0; ai < 2; ++ai)
; #pragma unroll
;             for (int m = 0; m < 4; ++m) { const size_t r = (size_t)(row0 + ai * 128 + m * 16);
; #pragma unroll
;                 for (int bj = 0; bj < 2; ++bj) { const int c = col0 + bj * 128; const v4u g = *(const v4u*)(P + pidx(r, 7680 + c));
;                     const f32x4 v0 = acc[ai][bj][m][0], v1 = acc[ai][bj][m][1];
;                     v4u w; w.x = pk2(v0[0] * lo_f(g.x), v0[1] * hi_f(g.x)); w.y = pk2(v0[2] * lo_f(g.y), v0[3] * hi_f(g.y)); w.z = pk2(v1[0] * lo_f(g.z), v1[1] * hi_f(g.z)); w.w = pk2(v1[2] * lo_f(g.w), v1[3] * hi_f(g.w));
;                     *(v4u*)(Y + r * 1024 + c) = w; } }
	v_lshlrev_b32_e32 v238, 16, v216
	v_and_b32_e32 v239, 0xffff0000, v216
	v_mul_f32_e32 v94, v94, v238
	v_mul_f32_e32 v95, v95, v239
	v_cvt_pk_bf16_f32 v244, v94, v95
	v_lshlrev_b32_e32 v238, 16, v217
	v_and_b32_e32 v239, 0xffff0000, v217
	v_mul_f32_e32 v96, v96, v238
	v_mul_f32_e32 v97, v97, v239
	v_cvt_pk_bf16_f32 v245, v96, v97
	v_lshlrev_b32_e32 v238, 16, v218
	v_and_b32_e32 v239, 0xffff0000, v218
	v_mul_f32_e32 v90, v90, v238
	v_mul_f32_e32 v91, v91, v239
	v_cvt_pk_bf16_f32 v246, v90, v91
	v_lshlrev_b32_e32 v238, 16, v219
	v_and_b32_e32 v239, 0xffff0000, v219
	v_mul_f32_e32 v92, v92, v238
	v_mul_f32_e32 v93, v93, v239
	v_cvt_pk_bf16_f32 v247, v92, v93
	s_mov_b64 s[98:99], 0x10000
	v_lshl_add_u64 v[236:237], v[232:233], 0, s[98:99]
	global_store_dwordx4 v[236:237], v[244:247], off
	s_mov_b64 s[98:99], 0x14000
	v_lshl_add_u64 v[234:235], v[150:151], 0, s[98:99]
	global_load_dwordx4 v[216:219], v[234:235], off
	s_waitcnt vmcnt(12)
	v_lshlrev_b32_e32 v238, 16, v220
	v_and_b32_e32 v239, 0xffff0000, v220
	v_mul_f32_e32 v86, v86, v238
	v_mul_f32_e32 v87, v87, v239
	v_cvt_pk_bf16_f32 v244, v86, v87
	v_lshlrev_b32_e32 v238, 16, v221
	v_and_b32_e32 v239, 0xffff0000, v221
	v_mul_f32_e32 v88, v88, v238
	v_mul_f32_e32 v89, v89, v239
	v_cvt_pk_bf16_f32 v245, v88, v89
	v_lshlrev_b32_e32 v238, 16, v222
	v_and_b32_e32 v239, 0xffff0000, v222
	v_mul_f32_e32 v82, v82, v238
	v_mul_f32_e32 v83, v83, v239
	v_cvt_pk_bf16_f32 v246, v82, v83
	v_lshlrev_b32_e32 v238, 16, v223
	v_and_b32_e32 v239, 0xffff0000, v223
	v_mul_f32_e32 v84, v84, v238
	v_mul_f32_e32 v85, v85, v239
	v_cvt_pk_bf16_f32 v247, v84, v85
	s_mov_b64 s[98:99], 0x10100
	v_lshl_add_u64 v[236:237], v[232:233], 0, s[98:99]
	global_store_dwordx4 v[236:237], v[244:247], off
	s_mov_b64 s[98:99], 0x14100
	v_lshl_add_u64 v[234:235], v[150:151], 0, s[98:99]
	global_load_dwordx4 v[220:223], v[234:235], off
	s_waitcnt vmcnt(13)
	v_lshlrev_b32_e32 v238, 16, v224
	v_and_b32_e32 v239, 0xffff0000, v224
	v_mul_f32_e32 v78, v78, v238
	v_mul_f32_e32 v79, v79, v239
	v_cvt_pk_bf16_f32 v244, v78, v79
	v_lshlrev_b32_e32 v238, 16, v225
	v_and_b32_e32 v239, 0xffff0000, v225
	v_mul_f32_e32 v80, v80, v238
	v_mul_f32_e32 v81, v81, v239
	v_cvt_pk_bf16_f32 v245, v80, v81
	v_lshlrev_b32_e32 v238, 16, v226
	v_and_b32_e32 v239, 0xffff0000, v226
	v_mul_f32_e32 v74, v74, v238
	v_mul_f32_e32 v75, v75, v239
	v_cvt_pk_bf16_f32 v246, v74, v75
	v_lshlrev_b32_e32 v238, 16, v227
	v_and_b32_e32 v239, 0xffff0000, v227
	v_mul_f32_e32 v76, v76, v238
	v_mul_f32_e32 v77, v77, v239
	v_cvt_pk_bf16_f32 v247, v76, v77
	s_mov_b64 s[98:99], 0x18000
	v_lshl_add_u64 v[236:237], v[232:233], 0, s[98:99]
	global_store_dwordx4 v[236:237], v[244:247], off
	s_mov_b64 s[98:99], 0x16000
	v_lshl_add_u64 v[234:235], v[150:151], 0, s[98:99]
	global_load_dwordx4 v[224:227], v[234:235], off
	s_waitcnt vmcnt(14)
	v_lshlrev_b32_e32 v238, 16, v228
	v_and_b32_e32 v239, 0xffff0000, v228
	v_mul_f32_e32 v70, v70, v238
	v_mul_f32_e32 v71, v71, v239
	v_cvt_pk_bf16_f32 v244, v70, v71
	v_lshlrev_b32_e32 v238, 16, v229
	v_and_b32_e32 v239, 0xffff0000, v229
	v_mul_f32_e32 v72, v72, v238
	v_mul_f32_e32 v73, v73, v239
	v_cvt_pk_bf16_f32 v245, v72, v73
	v_lshlrev_b32_e32 v238, 16, v230
	v_and_b32_e32 v239, 0xffff0000, v230
	v_mul_f32_e32 v66, v66, v238
	v_mul_f32_e32 v67, v67, v239
	v_cvt_pk_bf16_f32 v246, v66, v67
	v_lshlrev_b32_e32 v238, 16, v231
	v_and_b32_e32 v239, 0xffff0000, v231
	v_mul_f32_e32 v68, v68, v238
	v_mul_f32_e32 v69, v69, v239
	v_cvt_pk_bf16_f32 v247, v68, v69
	s_mov_b64 s[98:99], 0x18100
	v_lshl_add_u64 v[236:237], v[232:233], 0, s[98:99]
	global_store_dwordx4 v[236:237], v[244:247], off
	s_mov_b64 s[98:99], 0x16100
	v_lshl_add_u64 v[234:235], v[150:151], 0, s[98:99]
	global_load_dwordx4 v[228:231], v[234:235], off
	s_waitcnt vmcnt(14)
	v_lshlrev_b32_e32 v238, 16, v200
	v_and_b32_e32 v239, 0xffff0000, v200
	v_mul_f32_e32 v62, v62, v238
	v_mul_f32_e32 v63, v63, v239
	v_cvt_pk_bf16_f32 v244, v62, v63
	v_lshlrev_b32_e32 v238, 16, v201
	v_and_b32_e32 v239, 0xffff0000, v201
	v_mul_f32_e32 v64, v64, v238
	v_mul_f32_e32 v65, v65, v239
	v_cvt_pk_bf16_f32 v245, v64, v65
	v_lshlrev_b32_e32 v238, 16, v202
	v_and_b32_e32 v239, 0xffff0000, v202
	v_mul_f32_e32 v58, v58, v238
	v_mul_f32_e32 v59, v59, v239
	v_cvt_pk_bf16_f32 v246, v58, v59
	v_lshlrev_b32_e32 v238, 16, v203
	v_and_b32_e32 v239, 0xffff0000, v203
	v_mul_f32_e32 v60, v60, v238
	v_mul_f32_e32 v61, v61, v239
	v_cvt_pk_bf16_f32 v247, v60, v61
	s_mov_b64 s[98:99], 0x40000
	v_lshl_add_u64 v[236:237], v[232:233], 0, s[98:99]
	global_store_dwordx4 v[236:237], v[244:247], off
	s_nop 1
	s_waitcnt vmcnt(13)
	v_lshlrev_b32_e32 v238, 16, v204
	v_and_b32_e32 v239, 0xffff0000, v204
	v_mul_f32_e32 v54, v54, v238
	v_mul_f32_e32 v55, v55, v239
	v_cvt_pk_bf16_f32 v244, v54, v55
	v_lshlrev_b32_e32 v238, 16, v205
	v_and_b32_e32 v239, 0xffff0000, v205
	v_mul_f32_e32 v56, v56, v238
	v_mul_f32_e32 v57, v57, v239
	v_cvt_pk_bf16_f32 v245, v56, v57
	v_lshlrev_b32_e32 v238, 16, v206
	v_and_b32_e32 v239, 0xffff0000, v206
	v_mul_f32_e32 v50, v50, v238
	v_mul_f32_e32 v51, v51, v239
	v_cvt_pk_bf16_f32 v246, v50, v51
	v_lshlrev_b32_e32 v238, 16, v207
	v_and_b32_e32 v239, 0xffff0000, v207
	v_mul_f32_e32 v52, v52, v238
	v_mul_f32_e32 v53, v53, v239
	v_cvt_pk_bf16_f32 v247, v52, v53
	s_mov_b64 s[98:99], 0x40100
	v_lshl_add_u64 v[236:237], v[232:233], 0, s[98:99]
	global_store_dwordx4 v[236:237], v[244:247], off
	s_nop 1
	s_waitcnt vmcnt(12)
; DI size_t pidx(size_t row, int col) { return (size_t)(col >> 8) * ((size_t)TH * 256) + row * 256 + (size_t)(col & 255); }
; DI float lo_f(unsigned u) { return __uint_as_float(u << 16); }
; DI float hi_f(unsigned u) { return __uint_as_float(u & 0xffff0000u); }
; DI unsigned pk2(float lo, float hi) { return pg8::cvt_pk_bf16(lo, hi); }
;     DI void operator()(const f32x4 (&acc)[2][2][4][2], const Unit& u, int wr, int wc, int fr, int fq) const {
;     ...
;         for (int ai = 0; ai < 2; ++ai)
; #pragma unroll
;             for (int m = 0; m < 4; ++m) { const size_t r = (size_t)(row0 + ai * 128 + m * 16);
; #pragma unroll
;                 for (int bj = 0; bj < 2; ++bj) { const int c = col0 + bj * 128; const v4u g = *(const v4u*)(P + pidx(r, 7680 + c));
;                     const f32x4 v0 = acc[ai][bj][m][0], v1 = acc[ai][bj][m][1];
;                     v4u w; w.x = pk2(v0[0] * lo_f(g.x), v0[1] * hi_f(g.x)); w.y = pk2(v0[2] * lo_f(g.y), v0[3] * hi_f(g.y)); w.z = pk2(v1[0] * lo_f(g.z), v1[1] * hi_f(g.z)); w.w = pk2(v1[2] * lo_f(g.w), v1[3] * hi_f(g.w));
;                     *(v4u*)(Y + r * 1024 + c) = w; } }
	v_lshlrev_b32_e32 v238, 16, v208
	v_and_b32_e32 v239, 0xffff0000, v208
	v_mul_f32_e32 v46, v46, v238
	v_mul_f32_e32 v47, v47, v239
	v_cvt_pk_bf16_f32 v244, v46, v47
	v_lshlrev_b32_e32 v238, 16, v209
	v_and_b32_e32 v239, 0xffff0000, v209
	v_mul_f32_e32 v48, v48, v238
	v_mul_f32_e32 v49, v49, v239
	v_cvt_pk_bf16_f32 v245, v48, v49
	v_lshlrev_b32_e32 v238, 16, v210
	v_and_b32_e32 v239, 0xffff0000, v210
	v_mul_f32_e32 v42, v42, v238
	v_mul_f32_e32 v43, v43, v239
	v_cvt_pk_bf16_f32 v246, v42, v43
	v_lshlrev_b32_e32 v238, 16, v211
	v_and_b32_e32 v239, 0xffff0000, v211
	v_mul_f32_e32 v44, v44, v238
	v_mul_f32_e32 v45, v45, v239
	v_cvt_pk_bf16_f32 v247, v44, v45
	s_mov_b64 s[98:99], 0x48000
	v_lshl_add_u64 v[236:237], v[232:233], 0, s[98:99]
	global_store_dwordx4 v[236:237], v[244:247], off
	s_nop 1
	s_waitcnt vmcnt(11)
	v_lshlrev_b32_e32 v238, 16, v212
	v_and_b32_e32 v239, 0xffff0000, v212
	v_mul_f32_e32 v38, v38, v238
	v_mul_f32_e32 v39, v39, v239
	v_cvt_pk_bf16_f32 v244, v38, v39
	v_lshlrev_b32_e32 v238, 16, v213
	v_and_b32_e32 v239, 0xffff0000, v213
	v_mul_f32_e32 v40, v40, v238
	v_mul_f32_e32 v41, v41, v239
	v_cvt_pk_bf16_f32 v245, v40, v41
	v_lshlrev_b32_e32 v238, 16, v214
	v_and_b32_e32 v239, 0xffff0000, v214
	v_mul_f32_e32 v34, v34, v238
	v_mul_f32_e32 v35, v35, v239
	v_cvt_pk_bf16_f32 v246, v34, v35
	v_lshlrev_b32_e32 v238, 16, v215
	v_and_b32_e32 v239, 0xffff0000, v215
	v_mul_f32_e32 v36, v36, v238
	v_mul_f32_e32 v37, v37, v239
	v_cvt_pk_bf16_f32 v247, v36, v37
	s_mov_b64 s[98:99], 0x48100
	v_lshl_add_u64 v[236:237], v[232:233], 0, s[98:99]
	global_store_dwordx4 v[236:237], v[244:247], off
	s_nop 1
	s_waitcnt vmcnt(10)
	v_lshlrev_b32_e32 v238, 16, v216
	v_and_b32_e32 v239, 0xffff0000, v216
	v_mul_f32_e32 v30, v30, v238
	v_mul_f32_e32 v31, v31, v239
	v_cvt_pk_bf16_f32 v244, v30, v31
	v_lshlrev_b32_e32 v238, 16, v217
	v_and_b32_e32 v239, 0xffff0000, v217
	v_mul_f32_e32 v32, v32, v238
	v_mul_f32_e32 v33, v33, v239
	v_cvt_pk_bf16_f32 v245, v32, v33
	v_lshlrev_b32_e32 v238, 16, v218
	v_and_b32_e32 v239, 0xffff0000, v218
	v_mul_f32_e32 v26, v26, v238
	v_mul_f32_e32 v27, v27, v239
	v_cvt_pk_bf16_f32 v246, v26, v27
	v_lshlrev_b32_e32 v238, 16, v219
	v_and_b32_e32 v239, 0xffff0000, v219
	v_mul_f32_e32 v28, v28, v238
	v_mul_f32_e32 v29, v29, v239
	v_cvt_pk_bf16_f32 v247, v28, v29
	s_mov_b64 s[98:99], 0x50000
	v_lshl_add_u64 v[236:237], v[232:233], 0, s[98:99]
	global_store_dwordx4 v[236:237], v[244:247], off
	s_nop 1
	s_waitcnt vmcnt(9)
	v_lshlrev_b32_e32 v238, 16, v220
	v_and_b32_e32 v239, 0xffff0000, v220
	v_mul_f32_e32 v22, v22, v238
	v_mul_f32_e32 v23, v23, v239
	v_cvt_pk_bf16_f32 v244, v22, v23
	v_lshlrev_b32_e32 v238, 16, v221
	v_and_b32_e32 v239, 0xffff0000, v221
	v_mul_f32_e32 v24, v24, v238
	v_mul_f32_e32 v25, v25, v239
	v_cvt_pk_bf16_f32 v245, v24, v25
	v_lshlrev_b32_e32 v238, 16, v222
	v_and_b32_e32 v239, 0xffff0000, v222
	v_mul_f32_e32 v18, v18, v238
	v_mul_f32_e32 v19, v19, v239
	v_cvt_pk_bf16_f32 v246, v18, v19
	v_lshlrev_b32_e32 v238, 16, v223
	v_and_b32_e32 v239, 0xffff0000, v223
	v_mul_f32_e32 v20, v20, v238
	v_mul_f32_e32 v21, v21, v239
	v_cvt_pk_bf16_f32 v247, v20, v21
	s_mov_b64 s[98:99], 0x50100
	v_lshl_add_u64 v[236:237], v[232:233], 0, s[98:99]
	global_store_dwordx4 v[236:237], v[244:247], off
	s_nop 1
	s_waitcnt vmcnt(8)
	v_lshlrev_b32_e32 v238, 16, v224
	v_and_b32_e32 v239, 0xffff0000, v224
	v_mul_f32_e32 v14, v14, v238
	v_mul_f32_e32 v15, v15, v239
	v_cvt_pk_bf16_f32 v244, v14, v15
	v_lshlrev_b32_e32 v238, 16, v225
	v_and_b32_e32 v239, 0xffff0000, v225
	v_mul_f32_e32 v16, v16, v238
	v_mul_f32_e32 v17, v17, v239
	v_cvt_pk_bf16_f32 v245, v16, v17
	v_lshlrev_b32_e32 v238, 16, v226
	v_and_b32_e32 v239, 0xffff0000, v226
	v_mul_f32_e32 v10, v10, v238
	v_mul_f32_e32 v11, v11, v239
	v_cvt_pk_bf16_f32 v246, v10, v11
	v_lshlrev_b32_e32 v238, 16, v227
	v_and_b32_e32 v239, 0xffff0000, v227
	v_mul_f32_e32 v12, v12, v238
	v_mul_f32_e32 v13, v13, v239
	v_cvt_pk_bf16_f32 v247, v12, v13
	s_mov_b64 s[98:99], 0x58000
	v_lshl_add_u64 v[236:237], v[232:233], 0, s[98:99]
	global_store_dwordx4 v[236:237], v[244:247], off
	s_nop 1
	s_waitcnt vmcnt(7)
	v_lshlrev_b32_e32 v238, 16, v228
	v_and_b32_e32 v239, 0xffff0000, v228
	v_mul_f32_e32 v6, v6, v238
	v_mul_f32_e32 v7, v7, v239
	v_cvt_pk_bf16_f32 v244, v6, v7
	v_lshlrev_b32_e32 v238, 16, v229
	v_and_b32_e32 v239, 0xffff0000, v229
	v_mul_f32_e32 v8, v8, v238
	v_mul_f32_e32 v9, v9, v239
	v_cvt_pk_bf16_f32 v245, v8, v9
	v_lshlrev_b32_e32 v238, 16, v230
	v_and_b32_e32 v239, 0xffff0000, v230
	v_mul_f32_e32 v2, v2, v238
	v_mul_f32_e32 v3, v3, v239
	v_cvt_pk_bf16_f32 v246, v2, v3
	v_lshlrev_b32_e32 v238, 16, v231
	v_and_b32_e32 v239, 0xffff0000, v231
	v_mul_f32_e32 v4, v4, v238
	v_mul_f32_e32 v5, v5, v239
	v_cvt_pk_bf16_f32 v247, v4, v5
	s_mov_b64 s[98:99], 0x58100
	v_lshl_add_u64 v[236:237], v[232:233], 0, s[98:99]
	global_store_dwordx4 v[236:237], v[244:247], off
	s_nop 1
	s_mov_b64 s[2:3], -1
	s_cbranch_vccnz .LBB0_551
	s_andn2_b64 vcc, exec, s[6:7]
	s_cbranch_vccnz .LBB0_550
	s_barrier
	s_branch .LBB0_550

; DI size_t pidx(size_t row, int col) { return (size_t)(col >> 8) * ((size_t)TH * 256) + row * 256 + (size_t)(col & 255); }
; DI float lo_f(unsigned u) { return __uint_as_float(u << 16); }
; DI float hi_f(unsigned u) { return __uint_as_float(u & 0xffff0000u); }
; DI unsigned pk2(float lo, float hi) { return pg8::cvt_pk_bf16(lo, hi); }
;     DI void operator()(const f32x4 (&acc)[2][2][4][2], const Unit& u, int wr, int wc, int fr, int fq) const {
;         const int row0 = u.pm * 256 + wr * 64 + fr, col0 = u.pn * 256 + wc * 32 + 8 * fq;
; #pragma unroll
;         for (int ai = 0; ai < 2; ++ai)
; #pragma unroll
;             for (int m = 0; m < 4; ++m) { const size_t r = (size_t)(row0 + ai * 128 + m * 16);
; #pragma unroll
;                 for (int bj = 0; bj < 2; ++bj) { const int c = col0 + bj * 128; const v4u g = *(const v4u*)(P + pidx(r, 8704 + c)); const v4u y = *(const v4u*)(Y + r * 1024 + c);
;                     const f32x4 a0 = acc[ai][bj][m][0], a1 = acc[ai][bj][m][1];
;                     v4u w; w.x = pk2(lo_f(y.x) + a0[0] * lo_f(g.x), hi_f(y.x) + a0[1] * hi_f(g.x)); w.y = pk2(lo_f(y.y) + a0[2] * lo_f(g.y), hi_f(y.y) + a0[3] * hi_f(g.y));
;                     w.z = pk2(lo_f(y.z) + a1[0] * lo_f(g.z), hi_f(y.z) + a1[1] * hi_f(g.z)); w.w = pk2(lo_f(y.w) + a1[2] * lo_f(g.w), hi_f(y.w) + a1[3] * hi_f(g.w));
;                     *(v4u*)(Y + r * 1024 + c) = w; } }
.LBB0_582:
	s_lshl_b32 s9, s30, 8
	v_or_b32_e32 v146, s9, v138
	s_addk_i32 s9, 0x2200
	s_ashr_i32 s16, s9, 8
	s_ashr_i32 s17, s16, 31
	v_lshl_add_u32 v144, s31, 8, v139
	s_lshl_b64 s[16:17], s[16:17], 24
	v_ashrrev_i32_e32 v145, 31, v144
	s_add_u32 s16, s86, s16
	v_lshlrev_b64 v[148:149], 11, v[144:145]
	v_ashrrev_i32_e32 v147, 31, v146
	v_lshlrev_b64 v[156:157], 9, v[144:145]
	s_addc_u32 s17, s87, s17
	v_lshl_add_u64 v[148:149], s[88:89], 0, v[148:149]
	v_lshlrev_b64 v[146:147], 1, v[146:147]
	v_lshl_add_u64 v[160:161], s[16:17], 0, v[156:157]
	v_lshlrev_b32_e32 v0, 1, v138
	v_lshl_add_u64 v[148:149], v[148:149], 0, v[146:147]
	v_lshl_add_u64 v[156:157], v[160:161], 0, v[0:1]
	s_andn2_b64 vcc, exec, s[4:5]
	global_load_dwordx4 v[200:203], v[148:149], off
	global_load_dwordx4 v[204:207], v[156:157], off
	s_mov_b64 s[98:99], 0x100
	v_lshl_add_u64 v[232:233], v[148:149], 0, s[98:99]
	s_mov_b64 s[98:99], 0x100
	v_lshl_add_u64 v[234:235], v[156:157], 0, s[98:99]
	global_load_dwordx4 v[208:211], v[232:233], off
	global_load_dwordx4 v[212:215], v[234:235], off
	s_mov_b64 s[98:99], 0x8000
	v_lshl_add_u64 v[232:233], v[148:149], 0, s[98:99]
	s_mov_b64 s[98:99], 0x2000
	v_lshl_add_u64 v[234:235], v[156:157], 0, s[98:99]
	global_load_dwordx4 v[216:219], v[232:233], off
	global_load_dwordx4 v[220:223], v[234:235], off
	s_mov_b64 s[98:99], 0x8100
	v_lshl_add_u64 v[232:233], v[148:149], 0, s[98:99]
	s_mov_b64 s[98:99], 0x2100
	v_lshl_add_u64 v[234:235], v[156:157], 0, s[98:99]
	global_load_dwordx4 v[224:227], v[232:233], off
	global_load_dwordx4 v[228:231], v[234:235], off
	s_waitcnt vmcnt(6)
	v_lshlrev_b32_e32 v238, 16, v200
	v_and_b32_e32 v239, 0xffff0000, v200
	v_lshlrev_b32_e32 v244, 16, v204
	v_and_b32_e32 v245, 0xffff0000, v204
	v_fmac_f32_e32 v238, v126, v244
	v_fmac_f32_e32 v239, v127, v245
	v_cvt_pk_bf16_f32 v182, v238, v239
	v_lshlrev_b32_e32 v238, 16, v201
	v_and_b32_e32 v239, 0xffff0000, v201
	v_lshlrev_b32_e32 v244, 16, v205
	v_and_b32_e32 v245, 0xffff0000, v205
	v_fmac_f32_e32 v238, v128, v244
	v_fmac_f32_e32 v239, v129, v245
	v_cvt_pk_bf16_f32 v183, v238, v239
	v_lshlrev_b32_e32 v238, 16, v202
	v_and_b32_e32 v239, 0xffff0000, v202
	v_lshlrev_b32_e32 v244, 16, v206
	v_and_b32_e32 v245, 0xffff0000, v206
	v_fmac_f32_e32 v238, v122, v244
	v_fmac_f32_e32 v239, v123, v245
	v_cvt_pk_bf16_f32 v184, v238, v239
	v_lshlrev_b32_e32 v238, 16, v203
	v_and_b32_e32 v239, 0xffff0000, v203
	v_lshlrev_b32_e32 v244, 16, v207
	v_and_b32_e32 v245, 0xffff0000, v207
	v_fmac_f32_e32 v238, v124, v244
	v_fmac_f32_e32 v239, v125, v245
	v_cvt_pk_bf16_f32 v185, v238, v239
	global_store_dwordx4 v[148:149], v[182:185], off
	s_mov_b64 s[98:99], 0x10000
	v_lshl_add_u64 v[232:233], v[148:149], 0, s[98:99]
	s_mov_b64 s[98:99], 0x4000
	v_lshl_add_u64 v[234:235], v[156:157], 0, s[98:99]
	global_load_dwordx4 v[200:203], v[232:233], off
	global_load_dwordx4 v[204:207], v[234:235], off
	s_waitcnt vmcnt(7)
	v_lshlrev_b32_e32 v238, 16, v208
	v_and_b32_e32 v239, 0xffff0000, v208
	v_lshlrev_b32_e32 v244, 16, v212
	v_and_b32_e32 v245, 0xffff0000, v212
	v_fmac_f32_e32 v238, v118, v244
	v_fmac_f32_e32 v239, v119, v245
	v_cvt_pk_bf16_f32 v182, v238, v239
	v_lshlrev_b32_e32 v238, 16, v209
	v_and_b32_e32 v239, 0xffff0000, v209
	v_lshlrev_b32_e32 v244, 16, v213
	v_and_b32_e32 v245, 0xffff0000, v213
	v_fmac_f32_e32 v238, v120, v244
	v_fmac_f32_e32 v239, v121, v245
	v_cvt_pk_bf16_f32 v183, v238, v239
	v_lshlrev_b32_e32 v238, 16, v210
	v_and_b32_e32 v239, 0xffff0000, v210
	v_lshlrev_b32_e32 v244, 16, v214
	v_and_b32_e32 v245, 0xffff0000, v214
	v_fmac_f32_e32 v238, v114, v244
	v_fmac_f32_e32 v239, v115, v245
	v_cvt_pk_bf16_f32 v184, v238, v239
	v_lshlrev_b32_e32 v238, 16, v211
	v_and_b32_e32 v239, 0xffff0000, v211
	v_lshlrev_b32_e32 v244, 16, v215
	v_and_b32_e32 v245, 0xffff0000, v215
	v_fmac_f32_e32 v238, v116, v244
	v_fmac_f32_e32 v239, v117, v245
	v_cvt_pk_bf16_f32 v185, v238, v239
	s_mov_b64 s[98:99], 0x100
	v_lshl_add_u64 v[236:237], v[148:149], 0, s[98:99]
	global_store_dwordx4 v[236:237], v[182:185], off
	s_mov_b64 s[98:99], 0x10100
	v_lshl_add_u64 v[232:233], v[148:149], 0, s[98:99]
	s_mov_b64 s[98:99], 0x4100
	v_lshl_add_u64 v[234:235], v[156:157], 0, s[98:99]
	global_load_dwordx4 v[208:211], v[232:233], off
	global_load_dwordx4 v[212:215], v[234:235], off
	s_waitcnt vmcnt(8)
	v_lshlrev_b32_e32 v238, 16, v216
	v_and_b32_e32 v239, 0xffff0000, v216
	v_lshlrev_b32_e32 v244, 16, v220
	v_and_b32_e32 v245, 0xffff0000, v220
	v_fmac_f32_e32 v238, v110, v244
	v_fmac_f32_e32 v239, v111, v245
	v_cvt_pk_bf16_f32 v182, v238, v239
	v_lshlrev_b32_e32 v238, 16, v217
	v_and_b32_e32 v239, 0xffff0000, v217
	v_lshlrev_b32_e32 v244, 16, v221
	v_and_b32_e32 v245, 0xffff0000, v221
	v_fmac_f32_e32 v238, v112, v244
	v_fmac_f32_e32 v239, v113, v245
	v_cvt_pk_bf16_f32 v183, v238, v239
	v_lshlrev_b32_e32 v238, 16, v218
	v_and_b32_e32 v239, 0xffff0000, v218
	v_lshlrev_b32_e32 v244, 16, v222
	v_and_b32_e32 v245, 0xffff0000, v222
	v_fmac_f32_e32 v238, v106, v244
	v_fmac_f32_e32 v239, v107, v245
	v_cvt_pk_bf16_f32 v184, v238, v239
	v_lshlrev_b32_e32 v238, 16, v219
	v_and_b32_e32 v239, 0xffff0000, v219
	v_lshlrev_b32_e32 v244, 16, v223
	v_and_b32_e32 v245, 0xffff0000, v223
	v_fmac_f32_e32 v238, v108, v244
	v_fmac_f32_e32 v239, v109, v245
	v_cvt_pk_bf16_f32 v185, v238, v239
	s_mov_b64 s[98:99], 0x8000
	v_lshl_add_u64 v[236:237], v[148:149], 0, s[98:99]
	global_store_dwordx4 v[236:237], v[182:185], off
	s_mov_b64 s[98:99], 0x18000
	v_lshl_add_u64 v[232:233], v[148:149], 0, s[98:99]
	s_mov_b64 s[98:99], 0x6000
	v_lshl_add_u64 v[234:235], v[156:157], 0, s[98:99]
	global_load_dwordx4 v[216:219], v[232:233], off
	global_load_dwordx4 v[220:223], v[234:235], off
	s_waitcnt vmcnt(9)
; DI size_t pidx(size_t row, int col) { return (size_t)(col >> 8) * ((size_t)TH * 256) + row * 256 + (size_t)(col & 255); }
; DI float lo_f(unsigned u) { return __uint_as_float(u << 16); }
; DI float hi_f(unsigned u) { return __uint_as_float(u & 0xffff0000u); }
; DI unsigned pk2(float lo, float hi) { return pg8::cvt_pk_bf16(lo, hi); }
;     DI void operator()(const f32x4 (&acc)[2][2][4][2], const Unit& u, int wr, int wc, int fr, int fq) const {
;     ...
;         for (int ai = 0; ai < 2; ++ai)
; #pragma unroll
;             for (int m = 0; m < 4; ++m) { const size_t r = (size_t)(row0 + ai * 128 + m * 16);
; #pragma unroll
;                 for (int bj = 0; bj < 2; ++bj) { const int c = col0 + bj * 128; const v4u g = *(const v4u*)(P + pidx(r, 8704 + c)); const v4u y = *(const v4u*)(Y + r * 1024 + c);
;                     const f32x4 a0 = acc[ai][bj][m][0], a1 = acc[ai][bj][m][1];
;                     v4u w; w.x = pk2(lo_f(y.x) + a0[0] * lo_f(g.x), hi_f(y.x) + a0[1] * hi_f(g.x)); w.y = pk2(lo_f(y.y) + a0[2] * lo_f(g.y), hi_f(y.y) + a0[3] * hi_f(g.y));
;                     w.z = pk2(lo_f(y.z) + a1[0] * lo_f(g.z), hi_f(y.z) + a1[1] * hi_f(g.z)); w.w = pk2(lo_f(y.w) + a1[2] * lo_f(g.w), hi_f(y.w) + a1[3] * hi_f(g.w));
;                     *(v4u*)(Y + r * 1024 + c) = w; } }
	v_lshlrev_b32_e32 v238, 16, v224
	v_and_b32_e32 v239, 0xffff0000, v224
	v_lshlrev_b32_e32 v244, 16, v228
	v_and_b32_e32 v245, 0xffff0000, v228
	v_fmac_f32_e32 v238, v102, v244
	v_fmac_f32_e32 v239, v103, v245
	v_cvt_pk_bf16_f32 v182, v238, v239
	v_lshlrev_b32_e32 v238, 16, v225
	v_and_b32_e32 v239, 0xffff0000, v225
	v_lshlrev_b32_e32 v244, 16, v229
	v_and_b32_e32 v245, 0xffff0000, v229
	v_fmac_f32_e32 v238, v104, v244
	v_fmac_f32_e32 v239, v105, v245
	v_cvt_pk_bf16_f32 v183, v238, v239
	v_lshlrev_b32_e32 v238, 16, v226
	v_and_b32_e32 v239, 0xffff0000, v226
	v_lshlrev_b32_e32 v244, 16, v230
	v_and_b32_e32 v245, 0xffff0000, v230
	v_fmac_f32_e32 v238, v98, v244
	v_fmac_f32_e32 v239, v99, v245
	v_cvt_pk_bf16_f32 v184, v238, v239
	v_lshlrev_b32_e32 v238, 16, v227
	v_and_b32_e32 v239, 0xffff0000, v227
	v_lshlrev_b32_e32 v244, 16, v231
	v_and_b32_e32 v245, 0xffff0000, v231
	v_fmac_f32_e32 v238, v100, v244
	v_fmac_f32_e32 v239, v101, v245
	v_cvt_pk_bf16_f32 v185, v238, v239
	s_mov_b64 s[98:99], 0x8100
	v_lshl_add_u64 v[236:237], v[148:149], 0, s[98:99]
	global_store_dwordx4 v[236:237], v[182:185], off
	s_mov_b64 s[98:99], 0x18100
	v_lshl_add_u64 v[232:233], v[148:149], 0, s[98:99]
	s_mov_b64 s[98:99], 0x6100
	v_lshl_add_u64 v[234:235], v[156:157], 0, s[98:99]
	global_load_dwordx4 v[224:227], v[232:233], off
	global_load_dwordx4 v[228:231], v[234:235], off
	s_waitcnt vmcnt(9)
	v_lshlrev_b32_e32 v238, 16, v200
	v_and_b32_e32 v239, 0xffff0000, v200
	v_lshlrev_b32_e32 v244, 16, v204
	v_and_b32_e32 v245, 0xffff0000, v204
	v_fmac_f32_e32 v238, v94, v244
	v_fmac_f32_e32 v239, v95, v245
	v_cvt_pk_bf16_f32 v182, v238, v239
	v_lshlrev_b32_e32 v238, 16, v201
	v_and_b32_e32 v239, 0xffff0000, v201
	v_lshlrev_b32_e32 v244, 16, v205
	v_and_b32_e32 v245, 0xffff0000, v205
	v_fmac_f32_e32 v238, v96, v244
	v_fmac_f32_e32 v239, v97, v245
	v_cvt_pk_bf16_f32 v183, v238, v239
	v_lshlrev_b32_e32 v238, 16, v202
	v_and_b32_e32 v239, 0xffff0000, v202
	v_lshlrev_b32_e32 v244, 16, v206
	v_and_b32_e32 v245, 0xffff0000, v206
	v_fmac_f32_e32 v238, v90, v244
	v_fmac_f32_e32 v239, v91, v245
	v_cvt_pk_bf16_f32 v184, v238, v239
	v_lshlrev_b32_e32 v238, 16, v203
	v_and_b32_e32 v239, 0xffff0000, v203
	v_lshlrev_b32_e32 v244, 16, v207
	v_and_b32_e32 v245, 0xffff0000, v207
	v_fmac_f32_e32 v238, v92, v244
	v_fmac_f32_e32 v239, v93, v245
	v_cvt_pk_bf16_f32 v185, v238, v239
	s_mov_b64 s[98:99], 0x10000
	v_lshl_add_u64 v[236:237], v[148:149], 0, s[98:99]
	global_store_dwordx4 v[236:237], v[182:185], off
	s_mov_b64 s[98:99], 0x40000
	v_lshl_add_u64 v[232:233], v[148:149], 0, s[98:99]
	s_mov_b64 s[98:99], 0x10000
	v_lshl_add_u64 v[234:235], v[156:157], 0, s[98:99]
	global_load_dwordx4 v[200:203], v[232:233], off
	global_load_dwordx4 v[204:207], v[234:235], off
	s_waitcnt vmcnt(9)
	v_lshlrev_b32_e32 v238, 16, v208
	v_and_b32_e32 v239, 0xffff0000, v208
	v_lshlrev_b32_e32 v244, 16, v212
	v_and_b32_e32 v245, 0xffff0000, v212
	v_fmac_f32_e32 v238, v86, v244
	v_fmac_f32_e32 v239, v87, v245
	v_cvt_pk_bf16_f32 v182, v238, v239
	v_lshlrev_b32_e32 v238, 16, v209
	v_and_b32_e32 v239, 0xffff0000, v209
	v_lshlrev_b32_e32 v244, 16, v213
	v_and_b32_e32 v245, 0xffff0000, v213
	v_fmac_f32_e32 v238, v88, v244
	v_fmac_f32_e32 v239, v89, v245
	v_cvt_pk_bf16_f32 v183, v238, v239
	v_lshlrev_b32_e32 v238, 16, v210
	v_and_b32_e32 v239, 0xffff0000, v210
	v_lshlrev_b32_e32 v244, 16, v214
	v_and_b32_e32 v245, 0xffff0000, v214
	v_fmac_f32_e32 v238, v82, v244
	v_fmac_f32_e32 v239, v83, v245
	v_cvt_pk_bf16_f32 v184, v238, v239
	v_lshlrev_b32_e32 v238, 16, v211
	v_and_b32_e32 v239, 0xffff0000, v211
	v_lshlrev_b32_e32 v244, 16, v215
	v_and_b32_e32 v245, 0xffff0000, v215
	v_fmac_f32_e32 v238, v84, v244
	v_fmac_f32_e32 v239, v85, v245
	v_cvt_pk_bf16_f32 v185, v238, v239
	s_mov_b64 s[98:99], 0x10100
	v_lshl_add_u64 v[236:237], v[148:149], 0, s[98:99]
	global_store_dwordx4 v[236:237], v[182:185], off
	s_mov_b64 s[98:99], 0x40100
	v_lshl_add_u64 v[232:233], v[148:149], 0, s[98:99]
	s_mov_b64 s[98:99], 0x10100
	v_lshl_add_u64 v[234:235], v[156:157], 0, s[98:99]
	global_load_dwordx4 v[208:211], v[232:233], off
	global_load_dwordx4 v[212:215], v[234:235], off
	s_waitcnt vmcnt(9)
	v_lshlrev_b32_e32 v238, 16, v216
	v_and_b32_e32 v239, 0xffff0000, v216
	v_lshlrev_b32_e32 v244, 16, v220
	v_and_b32_e32 v245, 0xffff0000, v220
	v_fmac_f32_e32 v238, v78, v244
	v_fmac_f32_e32 v239, v79, v245
	v_cvt_pk_bf16_f32 v182, v238, v239
	v_lshlrev_b32_e32 v238, 16, v217
	v_and_b32_e32 v239, 0xffff0000, v217
	v_lshlrev_b32_e32 v244, 16, v221
	v_and_b32_e32 v245, 0xffff0000, v221
	v_fmac_f32_e32 v238, v80, v244
	v_fmac_f32_e32 v239, v81, v245
	v_cvt_pk_bf16_f32 v183, v238, v239
	v_lshlrev_b32_e32 v238, 16, v218
	v_and_b32_e32 v239, 0xffff0000, v218
	v_lshlrev_b32_e32 v244, 16, v222
	v_and_b32_e32 v245, 0xffff0000, v222
	v_fmac_f32_e32 v238, v74, v244
	v_fmac_f32_e32 v239, v75, v245
	v_cvt_pk_bf16_f32 v184, v238, v239
	v_lshlrev_b32_e32 v238, 16, v219
	v_and_b32_e32 v239, 0xffff0000, v219
	v_lshlrev_b32_e32 v244, 16, v223
	v_and_b32_e32 v245, 0xffff0000, v223
	v_fmac_f32_e32 v238, v76, v244
	v_fmac_f32_e32 v239, v77, v245
	v_cvt_pk_bf16_f32 v185, v238, v239
	s_mov_b64 s[98:99], 0x18000
	v_lshl_add_u64 v[236:237], v[148:149], 0, s[98:99]
	global_store_dwordx4 v[236:237], v[182:185], off
	s_mov_b64 s[98:99], 0x48000
	v_lshl_add_u64 v[232:233], v[148:149], 0, s[98:99]
	s_mov_b64 s[98:99], 0x12000
	v_lshl_add_u64 v[234:235], v[156:157], 0, s[98:99]
	global_load_dwordx4 v[216:219], v[232:233], off
	global_load_dwordx4 v[220:223], v[234:235], off
	s_waitcnt vmcnt(9)
; DI size_t pidx(size_t row, int col) { return (size_t)(col >> 8) * ((size_t)TH * 256) + row * 256 + (size_t)(col & 255); }
; DI float lo_f(unsigned u) { return __uint_as_float(u << 16); }
; DI float hi_f(unsigned u) { return __uint_as_float(u & 0xffff0000u); }
; DI unsigned pk2(float lo, float hi) { return pg8::cvt_pk_bf16(lo, hi); }
;     DI void operator()(const f32x4 (&acc)[2][2][4][2], const Unit& u, int wr, int wc, int fr, int fq) const {
;     ...
;         for (int ai = 0; ai < 2; ++ai)
; #pragma unroll
;             for (int m = 0; m < 4; ++m) { const size_t r = (size_t)(row0 + ai * 128 + m * 16);
; #pragma unroll
;                 for (int bj = 0; bj < 2; ++bj) { const int c = col0 + bj * 128; const v4u g = *(const v4u*)(P + pidx(r, 8704 + c)); const v4u y = *(const v4u*)(Y + r * 1024 + c);
;                     const f32x4 a0 = acc[ai][bj][m][0], a1 = acc[ai][bj][m][1];
;                     v4u w; w.x = pk2(lo_f(y.x) + a0[0] * lo_f(g.x), hi_f(y.x) + a0[1] * hi_f(g.x)); w.y = pk2(lo_f(y.y) + a0[2] * lo_f(g.y), hi_f(y.y) + a0[3] * hi_f(g.y));
;                     w.z = pk2(lo_f(y.z) + a1[0] * lo_f(g.z), hi_f(y.z) + a1[1] * hi_f(g.z)); w.w = pk2(lo_f(y.w) + a1[2] * lo_f(g.w), hi_f(y.w) + a1[3] * hi_f(g.w));
;                     *(v4u*)(Y + r * 1024 + c) = w; } }
	v_lshlrev_b32_e32 v238, 16, v224
	v_and_b32_e32 v239, 0xffff0000, v224
	v_lshlrev_b32_e32 v244, 16, v228
	v_and_b32_e32 v245, 0xffff0000, v228
	v_fmac_f32_e32 v238, v70, v244
	v_fmac_f32_e32 v239, v71, v245
	v_cvt_pk_bf16_f32 v182, v238, v239
	v_lshlrev_b32_e32 v238, 16, v225
	v_and_b32_e32 v239, 0xffff0000, v225
	v_lshlrev_b32_e32 v244, 16, v229
	v_and_b32_e32 v245, 0xffff0000, v229
	v_fmac_f32_e32 v238, v72, v244
	v_fmac_f32_e32 v239, v73, v245
	v_cvt_pk_bf16_f32 v183, v238, v239
	v_lshlrev_b32_e32 v238, 16, v226
	v_and_b32_e32 v239, 0xffff0000, v226
	v_lshlrev_b32_e32 v244, 16, v230
	v_and_b32_e32 v245, 0xffff0000, v230
	v_fmac_f32_e32 v238, v66, v244
	v_fmac_f32_e32 v239, v67, v245
	v_cvt_pk_bf16_f32 v184, v238, v239
	v_lshlrev_b32_e32 v238, 16, v227
	v_and_b32_e32 v239, 0xffff0000, v227
	v_lshlrev_b32_e32 v244, 16, v231
	v_and_b32_e32 v245, 0xffff0000, v231
	v_fmac_f32_e32 v238, v68, v244
	v_fmac_f32_e32 v239, v69, v245
	v_cvt_pk_bf16_f32 v185, v238, v239
	s_mov_b64 s[98:99], 0x18100
	v_lshl_add_u64 v[236:237], v[148:149], 0, s[98:99]
	global_store_dwordx4 v[236:237], v[182:185], off
	s_mov_b64 s[98:99], 0x48100
	v_lshl_add_u64 v[232:233], v[148:149], 0, s[98:99]
	s_mov_b64 s[98:99], 0x12100
	v_lshl_add_u64 v[234:235], v[156:157], 0, s[98:99]
	global_load_dwordx4 v[224:227], v[232:233], off
	global_load_dwordx4 v[228:231], v[234:235], off
	s_waitcnt vmcnt(9)
	v_lshlrev_b32_e32 v238, 16, v200
	v_and_b32_e32 v239, 0xffff0000, v200
	v_lshlrev_b32_e32 v244, 16, v204
	v_and_b32_e32 v245, 0xffff0000, v204
	v_fmac_f32_e32 v238, v62, v244
	v_fmac_f32_e32 v239, v63, v245
	v_cvt_pk_bf16_f32 v182, v238, v239
	v_lshlrev_b32_e32 v238, 16, v201
	v_and_b32_e32 v239, 0xffff0000, v201
	v_lshlrev_b32_e32 v244, 16, v205
	v_and_b32_e32 v245, 0xffff0000, v205
	v_fmac_f32_e32 v238, v64, v244
	v_fmac_f32_e32 v239, v65, v245
	v_cvt_pk_bf16_f32 v183, v238, v239
	v_lshlrev_b32_e32 v238, 16, v202
	v_and_b32_e32 v239, 0xffff0000, v202
	v_lshlrev_b32_e32 v244, 16, v206
	v_and_b32_e32 v245, 0xffff0000, v206
	v_fmac_f32_e32 v238, v58, v244
	v_fmac_f32_e32 v239, v59, v245
	v_cvt_pk_bf16_f32 v184, v238, v239
	v_lshlrev_b32_e32 v238, 16, v203
	v_and_b32_e32 v239, 0xffff0000, v203
	v_lshlrev_b32_e32 v244, 16, v207
	v_and_b32_e32 v245, 0xffff0000, v207
	v_fmac_f32_e32 v238, v60, v244
	v_fmac_f32_e32 v239, v61, v245
	v_cvt_pk_bf16_f32 v185, v238, v239
	s_mov_b64 s[98:99], 0x40000
	v_lshl_add_u64 v[236:237], v[148:149], 0, s[98:99]
	global_store_dwordx4 v[236:237], v[182:185], off
	s_mov_b64 s[98:99], 0x50000
	v_lshl_add_u64 v[232:233], v[148:149], 0, s[98:99]
	s_mov_b64 s[98:99], 0x14000
	v_lshl_add_u64 v[234:235], v[156:157], 0, s[98:99]
	global_load_dwordx4 v[200:203], v[232:233], off
	global_load_dwordx4 v[204:207], v[234:235], off
	s_waitcnt vmcnt(9)
	v_lshlrev_b32_e32 v238, 16, v208
	v_and_b32_e32 v239, 0xffff0000, v208
	v_lshlrev_b32_e32 v244, 16, v212
	v_and_b32_e32 v245, 0xffff0000, v212
	v_fmac_f32_e32 v238, v54, v244
	v_fmac_f32_e32 v239, v55, v245
	v_cvt_pk_bf16_f32 v182, v238, v239
	v_lshlrev_b32_e32 v238, 16, v209
	v_and_b32_e32 v239, 0xffff0000, v209
	v_lshlrev_b32_e32 v244, 16, v213
	v_and_b32_e32 v245, 0xffff0000, v213
	v_fmac_f32_e32 v238, v56, v244
	v_fmac_f32_e32 v239, v57, v245
	v_cvt_pk_bf16_f32 v183, v238, v239
	v_lshlrev_b32_e32 v238, 16, v210
	v_and_b32_e32 v239, 0xffff0000, v210
	v_lshlrev_b32_e32 v244, 16, v214
	v_and_b32_e32 v245, 0xffff0000, v214
	v_fmac_f32_e32 v238, v50, v244
	v_fmac_f32_e32 v239, v51, v245
	v_cvt_pk_bf16_f32 v184, v238, v239
	v_lshlrev_b32_e32 v238, 16, v211
	v_and_b32_e32 v239, 0xffff0000, v211
	v_lshlrev_b32_e32 v244, 16, v215
	v_and_b32_e32 v245, 0xffff0000, v215
	v_fmac_f32_e32 v238, v52, v244
	v_fmac_f32_e32 v239, v53, v245
	v_cvt_pk_bf16_f32 v185, v238, v239
	s_mov_b64 s[98:99], 0x40100
	v_lshl_add_u64 v[236:237], v[148:149], 0, s[98:99]
	global_store_dwordx4 v[236:237], v[182:185], off
	s_mov_b64 s[98:99], 0x50100
	v_lshl_add_u64 v[232:233], v[148:149], 0, s[98:99]
	s_mov_b64 s[98:99], 0x14100
	v_lshl_add_u64 v[234:235], v[156:157], 0, s[98:99]
	global_load_dwordx4 v[208:211], v[232:233], off
	global_load_dwordx4 v[212:215], v[234:235], off
	s_waitcnt vmcnt(9)
	v_lshlrev_b32_e32 v238, 16, v216
	v_and_b32_e32 v239, 0xffff0000, v216
	v_lshlrev_b32_e32 v244, 16, v220
	v_and_b32_e32 v245, 0xffff0000, v220
	v_fmac_f32_e32 v238, v46, v244
	v_fmac_f32_e32 v239, v47, v245
	v_cvt_pk_bf16_f32 v182, v238, v239
	v_lshlrev_b32_e32 v238, 16, v217
	v_and_b32_e32 v239, 0xffff0000, v217
	v_lshlrev_b32_e32 v244, 16, v221
	v_and_b32_e32 v245, 0xffff0000, v221
	v_fmac_f32_e32 v238, v48, v244
	v_fmac_f32_e32 v239, v49, v245
	v_cvt_pk_bf16_f32 v183, v238, v239
	v_lshlrev_b32_e32 v238, 16, v218
	v_and_b32_e32 v239, 0xffff0000, v218
	v_lshlrev_b32_e32 v244, 16, v222
	v_and_b32_e32 v245, 0xffff0000, v222
	v_fmac_f32_e32 v238, v42, v244
	v_fmac_f32_e32 v239, v43, v245
	v_cvt_pk_bf16_f32 v184, v238, v239
	v_lshlrev_b32_e32 v238, 16, v219
	v_and_b32_e32 v239, 0xffff0000, v219
	v_lshlrev_b32_e32 v244, 16, v223
	v_and_b32_e32 v245, 0xffff0000, v223
	v_fmac_f32_e32 v238, v44, v244
	v_fmac_f32_e32 v239, v45, v245
	v_cvt_pk_bf16_f32 v185, v238, v239
	s_mov_b64 s[98:99], 0x48000
	v_lshl_add_u64 v[236:237], v[148:149], 0, s[98:99]
	global_store_dwordx4 v[236:237], v[182:185], off
	s_mov_b64 s[98:99], 0x58000
	v_lshl_add_u64 v[232:233], v[148:149], 0, s[98:99]
	s_mov_b64 s[98:99], 0x16000
	v_lshl_add_u64 v[234:235], v[156:157], 0, s[98:99]
	global_load_dwordx4 v[216:219], v[232:233], off
	global_load_dwordx4 v[220:223], v[234:235], off
	s_waitcnt vmcnt(9)
; DI size_t pidx(size_t row, int col) { return (size_t)(col >> 8) * ((size_t)TH * 256) + row * 256 + (size_t)(col & 255); }
; DI float lo_f(unsigned u) { return __uint_as_float(u << 16); }
; DI float hi_f(unsigned u) { return __uint_as_float(u & 0xffff0000u); }
; DI unsigned pk2(float lo, float hi) { return pg8::cvt_pk_bf16(lo, hi); }
;     DI void operator()(const f32x4 (&acc)[2][2][4][2], const Unit& u, int wr, int wc, int fr, int fq) const {
;         const int row0 = u.pm * 256 + wr * 64 + fr, col0 = u.pn * 256 + wc * 32 + 8 * fq;
; #pragma unroll
;         for (int ai = 0; ai < 2; ++ai)
; #pragma unroll
;             for (int m = 0; m < 4; ++m) { const size_t r = (size_t)(row0 + ai * 128 + m * 16);
; #pragma unroll
;                 for (int bj = 0; bj < 2; ++bj) { const int c = col0 + bj * 128; const v4u g = *(const v4u*)(P + pidx(r, 8704 + c)); const v4u y = *(const v4u*)(Y + r * 1024 + c);
;                     const f32x4 a0 = acc[ai][bj][m][0], a1 = acc[ai][bj][m][1];
;                     v4u w; w.x = pk2(lo_f(y.x) + a0[0] * lo_f(g.x), hi_f(y.x) + a0[1] * hi_f(g.x)); w.y = pk2(lo_f(y.y) + a0[2] * lo_f(g.y), hi_f(y.y) + a0[3] * hi_f(g.y));
;                     w.z = pk2(lo_f(y.z) + a1[0] * lo_f(g.z), hi_f(y.z) + a1[1] * hi_f(g.z)); w.w = pk2(lo_f(y.w) + a1[2] * lo_f(g.w), hi_f(y.w) + a1[3] * hi_f(g.w));
;                     *(v4u*)(Y + r * 1024 + c) = w; } }
	v_lshlrev_b32_e32 v238, 16, v224
	v_and_b32_e32 v239, 0xffff0000, v224
	v_lshlrev_b32_e32 v244, 16, v228
	v_and_b32_e32 v245, 0xffff0000, v228
	v_fmac_f32_e32 v238, v38, v244
	v_fmac_f32_e32 v239, v39, v245
	v_cvt_pk_bf16_f32 v182, v238, v239
	v_lshlrev_b32_e32 v238, 16, v225
	v_and_b32_e32 v239, 0xffff0000, v225
	v_lshlrev_b32_e32 v244, 16, v229
	v_and_b32_e32 v245, 0xffff0000, v229
	v_fmac_f32_e32 v238, v40, v244
	v_fmac_f32_e32 v239, v41, v245
	v_cvt_pk_bf16_f32 v183, v238, v239
	v_lshlrev_b32_e32 v238, 16, v226
	v_and_b32_e32 v239, 0xffff0000, v226
	v_lshlrev_b32_e32 v244, 16, v230
	v_and_b32_e32 v245, 0xffff0000, v230
	v_fmac_f32_e32 v238, v34, v244
	v_fmac_f32_e32 v239, v35, v245
	v_cvt_pk_bf16_f32 v184, v238, v239
	v_lshlrev_b32_e32 v238, 16, v227
	v_and_b32_e32 v239, 0xffff0000, v227
	v_lshlrev_b32_e32 v244, 16, v231
	v_and_b32_e32 v245, 0xffff0000, v231
	v_fmac_f32_e32 v238, v36, v244
	v_fmac_f32_e32 v239, v37, v245
	v_cvt_pk_bf16_f32 v185, v238, v239
	s_mov_b64 s[98:99], 0x48100
	v_lshl_add_u64 v[236:237], v[148:149], 0, s[98:99]
	global_store_dwordx4 v[236:237], v[182:185], off
	s_mov_b64 s[98:99], 0x58100
	v_lshl_add_u64 v[232:233], v[148:149], 0, s[98:99]
	s_mov_b64 s[98:99], 0x16100
	v_lshl_add_u64 v[234:235], v[156:157], 0, s[98:99]
	global_load_dwordx4 v[224:227], v[232:233], off
	global_load_dwordx4 v[228:231], v[234:235], off
	s_waitcnt vmcnt(9)
	v_lshlrev_b32_e32 v238, 16, v200
	v_and_b32_e32 v239, 0xffff0000, v200
	v_lshlrev_b32_e32 v244, 16, v204
	v_and_b32_e32 v245, 0xffff0000, v204
	v_fmac_f32_e32 v238, v30, v244
	v_fmac_f32_e32 v239, v31, v245
	v_cvt_pk_bf16_f32 v182, v238, v239
	v_lshlrev_b32_e32 v238, 16, v201
	v_and_b32_e32 v239, 0xffff0000, v201
	v_lshlrev_b32_e32 v244, 16, v205
	v_and_b32_e32 v245, 0xffff0000, v205
	v_fmac_f32_e32 v238, v32, v244
	v_fmac_f32_e32 v239, v33, v245
	v_cvt_pk_bf16_f32 v183, v238, v239
	v_lshlrev_b32_e32 v238, 16, v202
	v_and_b32_e32 v239, 0xffff0000, v202
	v_lshlrev_b32_e32 v244, 16, v206
	v_and_b32_e32 v245, 0xffff0000, v206
	v_fmac_f32_e32 v238, v26, v244
	v_fmac_f32_e32 v239, v27, v245
	v_cvt_pk_bf16_f32 v184, v238, v239
	v_lshlrev_b32_e32 v238, 16, v203
	v_and_b32_e32 v239, 0xffff0000, v203
	v_lshlrev_b32_e32 v244, 16, v207
	v_and_b32_e32 v245, 0xffff0000, v207
	v_fmac_f32_e32 v238, v28, v244
	v_fmac_f32_e32 v239, v29, v245
	v_cvt_pk_bf16_f32 v185, v238, v239
	s_mov_b64 s[98:99], 0x50000
	v_lshl_add_u64 v[236:237], v[148:149], 0, s[98:99]
	global_store_dwordx4 v[236:237], v[182:185], off
	s_nop 1
	s_waitcnt vmcnt(7)
	v_lshlrev_b32_e32 v238, 16, v208
	v_and_b32_e32 v239, 0xffff0000, v208
	v_lshlrev_b32_e32 v244, 16, v212
	v_and_b32_e32 v245, 0xffff0000, v212
	v_fmac_f32_e32 v238, v22, v244
	v_fmac_f32_e32 v239, v23, v245
	v_cvt_pk_bf16_f32 v182, v238, v239
	v_lshlrev_b32_e32 v238, 16, v209
	v_and_b32_e32 v239, 0xffff0000, v209
	v_lshlrev_b32_e32 v244, 16, v213
	v_and_b32_e32 v245, 0xffff0000, v213
	v_fmac_f32_e32 v238, v24, v244
	v_fmac_f32_e32 v239, v25, v245
	v_cvt_pk_bf16_f32 v183, v238, v239
	v_lshlrev_b32_e32 v238, 16, v210
	v_and_b32_e32 v239, 0xffff0000, v210
	v_lshlrev_b32_e32 v244, 16, v214
	v_and_b32_e32 v245, 0xffff0000, v214
	v_fmac_f32_e32 v238, v18, v244
	v_fmac_f32_e32 v239, v19, v245
	v_cvt_pk_bf16_f32 v184, v238, v239
	v_lshlrev_b32_e32 v238, 16, v211
	v_and_b32_e32 v239, 0xffff0000, v211
	v_lshlrev_b32_e32 v244, 16, v215
	v_and_b32_e32 v245, 0xffff0000, v215
	v_fmac_f32_e32 v238, v20, v244
	v_fmac_f32_e32 v239, v21, v245
	v_cvt_pk_bf16_f32 v185, v238, v239
	s_mov_b64 s[98:99], 0x50100
	v_lshl_add_u64 v[236:237], v[148:149], 0, s[98:99]
	global_store_dwordx4 v[236:237], v[182:185], off
	s_nop 1
	s_waitcnt vmcnt(5)
	v_lshlrev_b32_e32 v238, 16, v216
	v_and_b32_e32 v239, 0xffff0000, v216
	v_lshlrev_b32_e32 v244, 16, v220
	v_and_b32_e32 v245, 0xffff0000, v220
	v_fmac_f32_e32 v238, v14, v244
	v_fmac_f32_e32 v239, v15, v245
	v_cvt_pk_bf16_f32 v182, v238, v239
	v_lshlrev_b32_e32 v238, 16, v217
	v_and_b32_e32 v239, 0xffff0000, v217
	v_lshlrev_b32_e32 v244, 16, v221
	v_and_b32_e32 v245, 0xffff0000, v221
	v_fmac_f32_e32 v238, v16, v244
	v_fmac_f32_e32 v239, v17, v245
	v_cvt_pk_bf16_f32 v183, v238, v239
	v_lshlrev_b32_e32 v238, 16, v218
	v_and_b32_e32 v239, 0xffff0000, v218
	v_lshlrev_b32_e32 v244, 16, v222
	v_and_b32_e32 v245, 0xffff0000, v222
	v_fmac_f32_e32 v238, v10, v244
	v_fmac_f32_e32 v239, v11, v245
	v_cvt_pk_bf16_f32 v184, v238, v239
	v_lshlrev_b32_e32 v238, 16, v219
	v_and_b32_e32 v239, 0xffff0000, v219
	v_lshlrev_b32_e32 v244, 16, v223
	v_and_b32_e32 v245, 0xffff0000, v223
	v_fmac_f32_e32 v238, v12, v244
	v_fmac_f32_e32 v239, v13, v245
	v_cvt_pk_bf16_f32 v185, v238, v239
	s_mov_b64 s[98:99], 0x58000
	v_lshl_add_u64 v[236:237], v[148:149], 0, s[98:99]
	global_store_dwordx4 v[236:237], v[182:185], off
	s_nop 1
	s_waitcnt vmcnt(3)
	v_lshlrev_b32_e32 v238, 16, v224
	v_and_b32_e32 v239, 0xffff0000, v224
	v_lshlrev_b32_e32 v244, 16, v228
	v_and_b32_e32 v245, 0xffff0000, v228
	v_fmac_f32_e32 v238, v6, v244
	v_fmac_f32_e32 v239, v7, v245
	v_cvt_pk_bf16_f32 v182, v238, v239
	v_lshlrev_b32_e32 v238, 16, v225
	v_and_b32_e32 v239, 0xffff0000, v225
	v_lshlrev_b32_e32 v244, 16, v229
	v_and_b32_e32 v245, 0xffff0000, v229
	v_fmac_f32_e32 v238, v8, v244
	v_fmac_f32_e32 v239, v9, v245
	v_cvt_pk_bf16_f32 v183, v238, v239
	v_lshlrev_b32_e32 v238, 16, v226
	v_and_b32_e32 v239, 0xffff0000, v226
	v_lshlrev_b32_e32 v244, 16, v230
	v_and_b32_e32 v245, 0xffff0000, v230
	v_fmac_f32_e32 v238, v2, v244
	v_fmac_f32_e32 v239, v3, v245
	v_cvt_pk_bf16_f32 v184, v238, v239
	v_lshlrev_b32_e32 v238, 16, v227
	v_and_b32_e32 v239, 0xffff0000, v227
	v_lshlrev_b32_e32 v244, 16, v231
	v_and_b32_e32 v245, 0xffff0000, v231
	v_fmac_f32_e32 v238, v4, v244
	v_fmac_f32_e32 v239, v5, v245
	v_cvt_pk_bf16_f32 v185, v238, v239
	s_mov_b64 s[98:99], 0x58100
	v_lshl_add_u64 v[236:237], v[148:149], 0, s[98:99]
	global_store_dwordx4 v[236:237], v[182:185], off
	s_nop 1
	s_movk_i32 s9, 0xf8
	s_mov_b64 s[4:5], -1
	s_cbranch_vccnz .LBB0_571
	s_andn2_b64 vcc, exec, s[2:3]
	s_cbranch_vccnz .LBB0_570
	s_barrier
	s_branch .LBB0_570
